# v16 + final-phase write-after-read guard checks the two y1 row panels its output tile overlaps (their finished-out-proj panel counters) instead of a stale pointer-relative address
# speedup vs baseline: 1.0069x; 1.0053x over previous
; __device__ __forceinline__ float bf_lo(unsigned w) { return __uint_as_float(w << 16); }
; __device__ __forceinline__ float bf_hi(unsigned w) { return __uint_as_float(w & 0xffff0000u); }
; __device__ __forceinline__ float fast_sigmoid(float v) { return __builtin_amdgcn_rcpf(1.0f + __builtin_amdgcn_exp2f(-1.4426950408889634f * v)); }
;     __device__ __forceinline__ void operator()(const Acc& acc, const Unit& u, int wr, int wc, int fr, int fq) const {
;         const int cb = u.pn * 256 + wc * 32 + 8 * fq;
; #pragma unroll
;         for (int ai = 0; ai < 2; ++ai) {
;             const size_t o0 = (size_t)(u.pm * 256 + ai * 128 + wr * 64 + fr) * DM + cb;
;             u32x4 xw[4][2], pw[4][2];
; #pragma unroll
;             for (int m = 0; m < 4; ++m)
; #pragma unroll
;                 for (int bj = 0; bj < 2; ++bj) { const size_t o = o0 + (size_t)m * 16 * DM + bj * 128; xw[m][bj] = *(const u32x4*)(xin + o); pw[m][bj] = *(const u32x4*)(pp + o); }
; #pragma unroll
;             for (int m = 0; m < 4; ++m)
; #pragma unroll
;                 for (int bj = 0; bj < 2; ++bj) {
;                     const size_t o = o0 + (size_t)m * 16 * DM + bj * 128;
;                     const u32x4 x = xw[m][bj], p = pw[m][bj];
;                     const f32x4 a0 = acc[ai][bj][m][0], a1 = acc[ai][bj][m][1];
;                     f32x4 r0, r1;
;                     r0[0] = bf_lo(x.x) + fast_sigmoid(a0[0]) * bf_lo(p.x); r0[1] = bf_hi(x.x) + fast_sigmoid(a0[1]) * bf_hi(p.x);
;                     r0[2] = bf_lo(x.y) + fast_sigmoid(a0[2]) * bf_lo(p.y); r0[3] = bf_hi(x.y) + fast_sigmoid(a0[3]) * bf_hi(p.y);
;                     r1[0] = bf_lo(x.z) + fast_sigmoid(a1[0]) * bf_lo(p.z); r1[1] = bf_hi(x.z) + fast_sigmoid(a1[1]) * bf_hi(p.z);
;                     r1[2] = bf_lo(x.w) + fast_sigmoid(a1[2]) * bf_lo(p.w); r1[3] = bf_hi(x.w) + fast_sigmoid(a1[3]) * bf_hi(p.w);
.LBB0_858:
	v_mov_b32_e32 v250, 8
	v_mov_b32_e32 v251, 8
	s_cmp_gt_u32 s42, 15
	s_cbranch_scc1 .Lp10_nog
	s_lshl_b32 s98, s42, 7
	s_add_i32 s98, s98, 0x3d0a404
	s_sub_u32 s100, s52, 0x8000000
	s_subb_u32 s101, s53, 0
	s_add_u32 s100, s100, s98
	s_addc_u32 s101, s101, 0
	v_mov_b32_e32 v252, s100
	v_mov_b32_e32 v253, s101
	global_load_dword v250, v[252:253], off sc1
	global_load_dword v251, v[252:253], off offset:64 sc1
.Lp10_nog:
	v_lshl_add_u32 v182, s42, 8, v184
	v_lshl_or_b32 v180, s63, 8, v186
	v_ashrrev_i32_e32 v183, 31, v182
	v_ashrrev_i32_e32 v181, 31, v180
	v_lshlrev_b64 v[128:129], 11, v[182:183]
	v_lshl_add_u64 v[218:219], v[128:129], 0, v[180:181]
	v_lshlrev_b64 v[128:129], 1, v[218:219]
	v_lshl_add_u64 v[130:131], s[52:53], 0, v[128:129]
	v_lshl_add_u64 v[132:133], s[6:7], 0, v[128:129]
	global_load_dwordx4 v[190:193], v[130:131], off
	global_load_dwordx4 v[194:197], v[132:133], off
	v_mul_f32_e32 v124, 0xbfb8aa3b, v124
	v_mul_f32_e32 v125, 0xbfb8aa3b, v125
	v_mul_f32_e32 v120, 0xbfb8aa3b, v120
	v_mul_f32_e32 v121, 0xbfb8aa3b, v121
	v_exp_f32_e32 v124, v124
	v_exp_f32_e32 v125, v125
	v_exp_f32_e32 v120, v120
	v_exp_f32_e32 v121, v121
	v_or_b32_e32 v128, 0x100, v128
	v_add_f32_e32 v134, 1.0, v124
	v_add_f32_e32 v135, 1.0, v125
	v_add_f32_e32 v138, 1.0, v120
	v_add_f32_e32 v139, 1.0, v121
	v_lshl_add_u64 v[120:121], s[52:53], 0, v[128:129]
	v_lshl_add_u64 v[124:125], s[6:7], 0, v[128:129]
	global_load_dwordx4 v[198:201], v[120:121], off
	global_load_dwordx4 v[202:205], v[124:125], off
	v_mul_f32_e32 v126, 0xbfb8aa3b, v126
	v_mul_f32_e32 v127, 0xbfb8aa3b, v127
	v_exp_f32_e32 v126, v126
	v_add_co_u32_e32 v120, vcc, s51, v130
	v_exp_f32_e32 v127, v127
	s_nop 0
	v_addc_co_u32_e32 v121, vcc, 0, v131, vcc
	v_add_co_u32_e32 v124, vcc, s51, v132
	v_add_f32_e32 v136, 1.0, v126
	s_nop 0
	v_addc_co_u32_e32 v125, vcc, 0, v133, vcc
	v_add_co_u32_e32 v126, vcc, s59, v130
	v_add_f32_e32 v137, 1.0, v127
	s_nop 0
	v_addc_co_u32_e32 v127, vcc, 0, v131, vcc
	v_add_co_u32_e32 v128, vcc, s59, v132
	v_rcp_f32_e32 v216, v134
	s_nop 0
	v_addc_co_u32_e32 v129, vcc, 0, v133, vcc
	v_add_co_u32_e32 v130, vcc, s60, v130
	v_rcp_f32_e32 v217, v135
	s_nop 0
	v_addc_co_u32_e32 v131, vcc, 0, v131, vcc
	v_add_co_u32_e32 v214, vcc, s60, v132
	v_rcp_f32_e32 v220, v136
	s_nop 0
	v_addc_co_u32_e32 v215, vcc, 0, v133, vcc
	v_rcp_f32_e32 v221, v137
	v_rcp_f32_e32 v222, v138
	v_rcp_f32_e32 v223, v139
	global_load_dwordx4 v[206:209], v[120:121], off
	global_load_dwordx4 v[160:163], v[120:121], off offset:256
	global_load_dwordx4 v[210:213], v[124:125], off
	global_load_dwordx4 v[156:159], v[124:125], off offset:256
	global_load_dwordx4 v[152:155], v[126:127], off
	global_load_dwordx4 v[144:147], v[126:127], off offset:256
	global_load_dwordx4 v[148:151], v[128:129], off
	global_load_dwordx4 v[140:143], v[128:129], off offset:256
	global_load_dwordx4 v[136:139], v[130:131], off
	s_nop 0
	global_load_dwordx4 v[128:131], v[130:131], off offset:256
	s_nop 0
	global_load_dwordx4 v[132:135], v[214:215], off
	global_load_dwordx4 v[124:127], v[214:215], off offset:256
	v_mul_f32_e32 v122, 0xbfb8aa3b, v122
	v_mul_f32_e32 v123, 0xbfb8aa3b, v123
	v_exp_f32_e32 v122, v122
	v_exp_f32_e32 v123, v123
	v_mul_f32_e32 v116, 0xbfb8aa3b, v116
	v_mul_f32_e32 v117, 0xbfb8aa3b, v117
	v_exp_f32_e32 v116, v116
	v_exp_f32_e32 v117, v117
	v_mul_f32_e32 v118, 0xbfb8aa3b, v118
	v_mul_f32_e32 v119, 0xbfb8aa3b, v119
	v_exp_f32_e32 v118, v118
	v_exp_f32_e32 v119, v119
	v_mul_f32_e32 v112, 0xbfb8aa3b, v112
	v_mul_f32_e32 v113, 0xbfb8aa3b, v113
	v_exp_f32_e32 v112, v112
	v_exp_f32_e32 v113, v113
	v_mul_f32_e32 v114, 0xbfb8aa3b, v114
	v_mul_f32_e32 v115, 0xbfb8aa3b, v115
	v_exp_f32_e32 v114, v114
	v_exp_f32_e32 v115, v115
	v_add_f32_e32 v116, 1.0, v116
	v_add_f32_e32 v117, 1.0, v117
	v_mul_f32_e32 v108, 0xbfb8aa3b, v108
	v_mul_f32_e32 v109, 0xbfb8aa3b, v109
	s_waitcnt vmcnt(0)
	s_mov_b32 s99, 0
.Lp10_gchk:
	v_readfirstlane_b32 s98, v250
	s_cmp_ge_u32 s98, 8
	s_cbranch_scc0 .Lp10_grt
	v_readfirstlane_b32 s98, v251
	s_cmp_ge_u32 s98, 8
	s_cbranch_scc1 .Lp10_gok
.Lp10_grt:
	s_sleep 1
	s_add_u32 s99, s99, 1
	s_cmp_gt_u32 s99, 0x40000
	s_cbranch_scc1 .Lp10_gok
	global_load_dword v250, v[252:253], off sc1
	global_load_dword v251, v[252:253], off offset:64 sc1
	s_waitcnt vmcnt(0)
	s_branch .Lp10_gchk
